# baseline (speedup 1.0000x reference)
.LBB0_373:
	s_waitcnt lgkmcnt(8)
	ds_read_b64_tr_b16 v[240:241], v212 offset:2048
	ds_read_b64_tr_b16 v[242:243], v212 offset:6144
	ds_read_b64_tr_b16 v[244:245], v212 offset:10240
	ds_read_b64_tr_b16 v[246:247], v212 offset:14336
	v_mfma_f32_16x16x32_bf16 v[52:55], v[120:123], v[136:139], v[52:55]
	v_exp_f32_e32 v162, v84
	v_exp_f32_e32 v163, v85
	v_mfma_f32_16x16x32_bf16 v[48:51], v[124:127], v[136:139], v[48:51]
	v_exp_f32_e32 v161, v86
	v_exp_f32_e32 v160, v87
	v_mfma_f32_16x16x32_bf16 v[52:55], v[112:115], v[148:151], v[52:55]
	v_exp_f32_e32 v167, v96
	v_mfma_f32_16x16x32_bf16 v[48:51], v[116:119], v[148:151], v[48:51]
	v_exp_f32_e32 v166, v97
	s_waitcnt lgkmcnt(8)
	ds_read_b64_tr_b16 v[128:129], v213 offset:2048
	ds_read_b64_tr_b16 v[130:131], v213 offset:6144
	ds_read_b64_tr_b16 v[132:133], v213 offset:10240
	ds_read_b64_tr_b16 v[134:135], v213 offset:14336
	v_mfma_f32_16x16x32_bf16 v[44:47], v[120:123], v[152:155], v[44:47]
	v_exp_f32_e32 v164, v98
	v_exp_f32_e32 v165, v99
	v_mfma_f32_16x16x32_bf16 v[40:43], v[124:127], v[152:155], v[40:43]
	v_exp_f32_e32 v171, v100
	v_exp_f32_e32 v170, v101
	v_mfma_f32_16x16x32_bf16 v[44:47], v[112:115], v[156:159], v[44:47]
	v_exp_f32_e32 v169, v102
	v_mfma_f32_16x16x32_bf16 v[40:43], v[116:119], v[156:159], v[40:43]
	v_exp_f32_e32 v168, v103
	s_waitcnt lgkmcnt(8)
	ds_read_b64_tr_b16 v[136:137], v212 offset:3072
	ds_read_b64_tr_b16 v[138:139], v212 offset:7168
	ds_read_b64_tr_b16 v[148:149], v212 offset:11264
	ds_read_b64_tr_b16 v[150:151], v212 offset:15360
	v_mfma_f32_16x16x32_bf16 v[32:35], v[120:123], v[140:143], v[32:35]
	v_exp_f32_e32 v178, v108
	v_exp_f32_e32 v179, v109
	v_mfma_f32_16x16x32_bf16 v[36:39], v[124:127], v[140:143], v[36:39]
	v_exp_f32_e32 v177, v110
	v_exp_f32_e32 v176, v111
	v_mfma_f32_16x16x32_bf16 v[32:35], v[112:115], v[144:147], v[32:35]
	v_exp_f32_e32 v175, v80
	v_mfma_f32_16x16x32_bf16 v[36:39], v[116:119], v[144:147], v[36:39]
	v_exp_f32_e32 v174, v81
	s_waitcnt lgkmcnt(8)
	ds_read_b64_tr_b16 v[152:153], v213 offset:3072
	ds_read_b64_tr_b16 v[154:155], v213 offset:7168
	ds_read_b64_tr_b16 v[156:157], v213 offset:11264
	ds_read_b64_tr_b16 v[158:159], v213 offset:15360
	v_mfma_f32_16x16x32_bf16 v[20:23], v[120:123], v[240:243], v[20:23]
	v_exp_f32_e32 v172, v82
	v_exp_f32_e32 v173, v83
	v_mfma_f32_16x16x32_bf16 v[16:19], v[124:127], v[240:243], v[16:19]
	v_exp_f32_e32 v183, v88
	v_exp_f32_e32 v182, v89
	v_mfma_f32_16x16x32_bf16 v[20:23], v[112:115], v[244:247], v[20:23]
	v_exp_f32_e32 v181, v90
	v_mfma_f32_16x16x32_bf16 v[16:19], v[116:119], v[244:247], v[16:19]
	v_exp_f32_e32 v180, v91
	s_waitcnt lgkmcnt(8)
	v_mfma_f32_16x16x32_bf16 v[28:31], v[120:123], v[128:131], v[28:31]
	v_exp_f32_e32 v186, v92
	v_mfma_f32_16x16x32_bf16 v[24:27], v[124:127], v[128:131], v[24:27]
	v_exp_f32_e32 v187, v93
	v_mfma_f32_16x16x32_bf16 v[28:31], v[112:115], v[132:135], v[28:31]
	v_exp_f32_e32 v185, v94
	v_mfma_f32_16x16x32_bf16 v[24:27], v[116:119], v[132:135], v[24:27]
	v_exp_f32_e32 v184, v95
	s_waitcnt lgkmcnt(4)
	v_mfma_f32_16x16x32_bf16 v[12:15], v[120:123], v[136:139], v[12:15]
	v_exp_f32_e32 v191, v104
	v_mfma_f32_16x16x32_bf16 v[8:11], v[124:127], v[136:139], v[8:11]
	v_exp_f32_e32 v190, v105
	v_mfma_f32_16x16x32_bf16 v[12:15], v[112:115], v[148:151], v[12:15]
	v_mfma_f32_16x16x32_bf16 v[8:11], v[116:119], v[148:151], v[8:11]
	s_waitcnt lgkmcnt(0)
	v_mfma_f32_16x16x32_bf16 v[4:7], v[120:123], v[152:155], v[4:7]
	v_exp_f32_e32 v189, v106
	v_mfma_f32_16x16x32_bf16 v[0:3], v[124:127], v[152:155], v[0:3]
	v_exp_f32_e32 v188, v107
	v_mfma_f32_16x16x32_bf16 v[4:7], v[112:115], v[156:159], v[4:7]
	v_mfma_f32_16x16x32_bf16 v[0:3], v[116:119], v[156:159], v[0:3]
	s_waitcnt vmcnt(3)
	s_waitcnt lgkmcnt(0)
	s_add_i32 s0, s23, 1
	s_cmp_ge_i32 s0, s14
	s_mov_b64 s[0:1], -1
	s_barrier
	s_cbranch_scc1 .LBB0_368
	s_and_b32 s0, s20, 0x6000
	v_add_u32_e32 v84, s0, v229
	v_add_u32_e32 v86, v84, v230
	v_add_u32_e32 v87, v84, v231
	ds_read_b128 v[240:243], v228
	ds_read_b128 v[128:131], v86
	ds_read_b128 v[244:247], v228 offset:2048
	ds_read_b128 v[132:135], v87
	ds_read_b128 v[152:155], v228 offset:1024
	ds_read_b128 v[156:159], v228 offset:3072
	ds_read_b128 v[136:139], v86 offset:512
	ds_read_b128 v[148:151], v87 offset:512
	ds_read_b128 v[140:143], v86 offset:4096
	ds_read_b128 v[144:147], v87 offset:4096
	s_lshl_b32 s0, s22, 14
	v_add_u32_e32 v214, s0, v223
	v_add_u32_e32 v215, s0, v224
	v_cvt_pk_bf16_f32 v120, v162, v163
	v_cvt_pk_bf16_f32 v121, v161, v160
	v_cvt_pk_bf16_f32 v122, v167, v166
	v_cvt_pk_bf16_f32 v123, v164, v165
	v_cvt_pk_bf16_f32 v112, v171, v170
	v_cvt_pk_bf16_f32 v113, v169, v168
	v_cvt_pk_bf16_f32 v114, v178, v179
	v_cvt_pk_bf16_f32 v115, v177, v176
	v_cvt_pk_bf16_f32 v124, v175, v174
	v_cvt_pk_bf16_f32 v125, v172, v173
	v_cvt_pk_bf16_f32 v126, v183, v182
	v_cvt_pk_bf16_f32 v127, v181, v180
	v_cvt_pk_bf16_f32 v116, v186, v187
	v_cvt_pk_bf16_f32 v117, v185, v184
	v_cvt_pk_bf16_f32 v118, v191, v190
	v_cvt_pk_bf16_f32 v119, v189, v188
	s_andn2_b64 vcc, exec, s[12:13]
	s_cbranch_vccz .Lh2a_resc

; DEV void diff16_pass(const bf16_t* __restrict__ proj, int qcol, int kcol, int vcol, int q0, f32x4 (&o)[2][8], f32x4 (&l_out)[2], unsigned char* lds) {
;     ...
;   for (int j = 1; j < NT; j += 2) {
;     HALF16(SB2, alB, rfB, SA, alA, rfA, j);
;     if (j + 1 >= NT) break;
;     HALF16(SA, alA, rfA, SB2, alB, rfB, j + 1);
;   }
.LBB0_390:
	s_waitcnt lgkmcnt(8)
	ds_read_b64_tr_b16 v[160:161], v214 offset:2048
	ds_read_b64_tr_b16 v[162:163], v214 offset:6144
	ds_read_b64_tr_b16 v[164:165], v214 offset:10240
	ds_read_b64_tr_b16 v[166:167], v214 offset:14336
	v_mfma_f32_16x16x32_bf16 v[52:55], v[120:123], v[176:179], v[52:55]
	v_exp_f32_e32 v241, v84
	v_exp_f32_e32 v244, v85
	v_mfma_f32_16x16x32_bf16 v[48:51], v[124:127], v[176:179], v[48:51]
	v_exp_f32_e32 v245, v86
	v_exp_f32_e32 v247, v87
	v_mfma_f32_16x16x32_bf16 v[52:55], v[112:115], v[180:183], v[52:55]
	v_exp_f32_e32 v240, v96
	v_mfma_f32_16x16x32_bf16 v[48:51], v[116:119], v[180:183], v[48:51]
	v_exp_f32_e32 v242, v97
	s_waitcnt lgkmcnt(8)
	ds_read_b64_tr_b16 v[168:169], v215 offset:2048
	ds_read_b64_tr_b16 v[170:171], v215 offset:6144
	ds_read_b64_tr_b16 v[172:173], v215 offset:10240
	ds_read_b64_tr_b16 v[174:175], v215 offset:14336
	v_mfma_f32_16x16x32_bf16 v[44:47], v[120:123], v[184:187], v[44:47]
	v_exp_f32_e32 v243, v98
	v_exp_f32_e32 v246, v99
	v_mfma_f32_16x16x32_bf16 v[40:43], v[124:127], v[184:187], v[40:43]
	v_exp_f32_e32 v137, v80
	v_exp_f32_e32 v148, v81
	v_mfma_f32_16x16x32_bf16 v[44:47], v[112:115], v[188:191], v[44:47]
	v_exp_f32_e32 v149, v82
	v_mfma_f32_16x16x32_bf16 v[40:43], v[116:119], v[188:191], v[40:43]
	v_exp_f32_e32 v151, v83
	s_waitcnt lgkmcnt(8)
	ds_read_b64_tr_b16 v[176:177], v214 offset:3072
	ds_read_b64_tr_b16 v[178:179], v214 offset:7168
	ds_read_b64_tr_b16 v[180:181], v214 offset:11264
	ds_read_b64_tr_b16 v[182:183], v214 offset:15360
	v_mfma_f32_16x16x32_bf16 v[32:35], v[120:123], v[140:143], v[32:35]
	v_exp_f32_e32 v136, v89
	v_exp_f32_e32 v139, v90
	v_mfma_f32_16x16x32_bf16 v[36:39], v[124:127], v[140:143], v[36:39]
	v_exp_f32_e32 v150, v91
	v_exp_f32_e32 v129, v92
	v_mfma_f32_16x16x32_bf16 v[32:35], v[112:115], v[144:147], v[32:35]
	v_exp_f32_e32 v138, v95
	v_mfma_f32_16x16x32_bf16 v[36:39], v[116:119], v[144:147], v[36:39]
	v_exp_f32_e32 v128, v104
	s_waitcnt lgkmcnt(8)
	ds_read_b64_tr_b16 v[184:185], v215 offset:3072
	ds_read_b64_tr_b16 v[186:187], v215 offset:7168
	ds_read_b64_tr_b16 v[188:189], v215 offset:11264
	ds_read_b64_tr_b16 v[190:191], v215 offset:15360
	v_mfma_f32_16x16x32_bf16 v[20:23], v[120:123], v[160:163], v[20:23]
	v_exp_f32_e32 v130, v105
	v_exp_f32_e32 v131, v106
	v_mfma_f32_16x16x32_bf16 v[16:19], v[124:127], v[160:163], v[16:19]
	v_exp_f32_e32 v153, v100
	v_exp_f32_e32 v152, v108
	v_mfma_f32_16x16x32_bf16 v[20:23], v[112:115], v[164:167], v[20:23]
	v_exp_f32_e32 v154, v109
	v_mfma_f32_16x16x32_bf16 v[16:19], v[116:119], v[164:167], v[16:19]
	v_exp_f32_e32 v155, v110
	s_waitcnt lgkmcnt(8)
	v_mfma_f32_16x16x32_bf16 v[28:31], v[120:123], v[168:171], v[28:31]
	v_exp_f32_e32 v156, v101
	v_mfma_f32_16x16x32_bf16 v[24:27], v[124:127], v[168:171], v[24:27]
	v_exp_f32_e32 v158, v102
	v_mfma_f32_16x16x32_bf16 v[28:31], v[112:115], v[172:175], v[28:31]
	v_exp_f32_e32 v159, v103
	v_mfma_f32_16x16x32_bf16 v[24:27], v[116:119], v[172:175], v[24:27]
	v_exp_f32_e32 v157, v111
	s_waitcnt lgkmcnt(4)
	v_mfma_f32_16x16x32_bf16 v[12:15], v[120:123], v[176:179], v[12:15]
	v_exp_f32_e32 v132, v88
	v_mfma_f32_16x16x32_bf16 v[8:11], v[124:127], v[176:179], v[8:11]
	v_exp_f32_e32 v134, v93
	v_mfma_f32_16x16x32_bf16 v[12:15], v[112:115], v[180:183], v[12:15]
	v_mfma_f32_16x16x32_bf16 v[8:11], v[116:119], v[180:183], v[8:11]
	s_waitcnt lgkmcnt(0)
	v_mfma_f32_16x16x32_bf16 v[4:7], v[120:123], v[184:187], v[4:7]
	v_exp_f32_e32 v135, v94
	v_mfma_f32_16x16x32_bf16 v[0:3], v[124:127], v[184:187], v[0:3]
	v_exp_f32_e32 v133, v107
	v_mfma_f32_16x16x32_bf16 v[4:7], v[112:115], v[188:191], v[4:7]
	v_mfma_f32_16x16x32_bf16 v[0:3], v[116:119], v[188:191], v[0:3]
	s_waitcnt vmcnt(3)
	s_waitcnt lgkmcnt(0)
	s_add_i32 s19, s19, 0x8000
	s_addk_i32 s20, 0x4000
	s_cmp_ge_i32 s21, s14
	s_cselect_b64 s[0:1], -1, 0
	s_barrier
	s_and_b64 vcc, exec, s[0:1]
	s_mov_b32 s23, s21
	s_cbranch_vccz .LBB0_369
	s_branch .LBB0_392

.LBB0_400:
	s_waitcnt lgkmcnt(8)
	ds_read_b64_tr_b16 v[240:241], v212 offset:2048
	ds_read_b64_tr_b16 v[242:243], v212 offset:6144
	ds_read_b64_tr_b16 v[244:245], v212 offset:10240
	ds_read_b64_tr_b16 v[246:247], v212 offset:14336
	v_mfma_f32_16x16x32_bf16 v[52:55], v[120:123], v[136:139], v[52:55]
	v_exp_f32_e32 v162, v84
	v_exp_f32_e32 v163, v85
	v_mfma_f32_16x16x32_bf16 v[48:51], v[124:127], v[136:139], v[48:51]
	v_exp_f32_e32 v161, v86
	v_exp_f32_e32 v160, v87
	v_mfma_f32_16x16x32_bf16 v[52:55], v[112:115], v[148:151], v[52:55]
	v_exp_f32_e32 v167, v96
	v_mfma_f32_16x16x32_bf16 v[48:51], v[116:119], v[148:151], v[48:51]
	v_exp_f32_e32 v166, v97
	s_waitcnt lgkmcnt(8)
	ds_read_b64_tr_b16 v[128:129], v213 offset:2048
	ds_read_b64_tr_b16 v[130:131], v213 offset:6144
	ds_read_b64_tr_b16 v[132:133], v213 offset:10240
	ds_read_b64_tr_b16 v[134:135], v213 offset:14336
	v_mfma_f32_16x16x32_bf16 v[44:47], v[120:123], v[152:155], v[44:47]
	v_exp_f32_e32 v164, v98
	v_exp_f32_e32 v165, v99
	v_mfma_f32_16x16x32_bf16 v[40:43], v[124:127], v[152:155], v[40:43]
	v_exp_f32_e32 v171, v100
	v_exp_f32_e32 v170, v101
	v_mfma_f32_16x16x32_bf16 v[44:47], v[112:115], v[156:159], v[44:47]
	v_exp_f32_e32 v169, v102
	v_mfma_f32_16x16x32_bf16 v[40:43], v[116:119], v[156:159], v[40:43]
	v_exp_f32_e32 v168, v103
	s_waitcnt lgkmcnt(8)
	ds_read_b64_tr_b16 v[136:137], v212 offset:3072
	ds_read_b64_tr_b16 v[138:139], v212 offset:7168
	ds_read_b64_tr_b16 v[148:149], v212 offset:11264
	ds_read_b64_tr_b16 v[150:151], v212 offset:15360
	v_mfma_f32_16x16x32_bf16 v[32:35], v[120:123], v[140:143], v[32:35]
	v_exp_f32_e32 v178, v108
	v_exp_f32_e32 v179, v109
	v_mfma_f32_16x16x32_bf16 v[36:39], v[124:127], v[140:143], v[36:39]
	v_exp_f32_e32 v177, v110
	v_exp_f32_e32 v176, v111
	v_mfma_f32_16x16x32_bf16 v[32:35], v[112:115], v[144:147], v[32:35]
	v_exp_f32_e32 v175, v80
	v_mfma_f32_16x16x32_bf16 v[36:39], v[116:119], v[144:147], v[36:39]
	v_exp_f32_e32 v174, v81
	s_waitcnt lgkmcnt(8)
	ds_read_b64_tr_b16 v[152:153], v213 offset:3072
	ds_read_b64_tr_b16 v[154:155], v213 offset:7168
	ds_read_b64_tr_b16 v[156:157], v213 offset:11264
	ds_read_b64_tr_b16 v[158:159], v213 offset:15360
	v_mfma_f32_16x16x32_bf16 v[20:23], v[120:123], v[240:243], v[20:23]
	v_exp_f32_e32 v172, v82
	v_exp_f32_e32 v173, v83
	v_mfma_f32_16x16x32_bf16 v[16:19], v[124:127], v[240:243], v[16:19]
	v_exp_f32_e32 v183, v88
	v_exp_f32_e32 v182, v89
	v_mfma_f32_16x16x32_bf16 v[20:23], v[112:115], v[244:247], v[20:23]
	v_exp_f32_e32 v181, v90
	v_mfma_f32_16x16x32_bf16 v[16:19], v[116:119], v[244:247], v[16:19]
	v_exp_f32_e32 v180, v91
	s_waitcnt lgkmcnt(8)
	v_mfma_f32_16x16x32_bf16 v[28:31], v[120:123], v[128:131], v[28:31]
	v_exp_f32_e32 v186, v92
	v_mfma_f32_16x16x32_bf16 v[24:27], v[124:127], v[128:131], v[24:27]
	v_exp_f32_e32 v187, v93
	v_mfma_f32_16x16x32_bf16 v[28:31], v[112:115], v[132:135], v[28:31]
	v_exp_f32_e32 v185, v94
	v_mfma_f32_16x16x32_bf16 v[24:27], v[116:119], v[132:135], v[24:27]
	v_exp_f32_e32 v184, v95
	s_waitcnt lgkmcnt(4)
	v_mfma_f32_16x16x32_bf16 v[12:15], v[120:123], v[136:139], v[12:15]
	v_exp_f32_e32 v191, v104
	v_mfma_f32_16x16x32_bf16 v[8:11], v[124:127], v[136:139], v[8:11]
	v_exp_f32_e32 v190, v105
	v_mfma_f32_16x16x32_bf16 v[12:15], v[112:115], v[148:151], v[12:15]
	v_mfma_f32_16x16x32_bf16 v[8:11], v[116:119], v[148:151], v[8:11]
	s_waitcnt lgkmcnt(0)
	v_mfma_f32_16x16x32_bf16 v[4:7], v[120:123], v[152:155], v[4:7]
	v_exp_f32_e32 v189, v106
	v_mfma_f32_16x16x32_bf16 v[0:3], v[124:127], v[152:155], v[0:3]
	v_exp_f32_e32 v188, v107
	v_mfma_f32_16x16x32_bf16 v[4:7], v[112:115], v[156:159], v[4:7]
	v_mfma_f32_16x16x32_bf16 v[0:3], v[116:119], v[156:159], v[0:3]
	s_waitcnt vmcnt(3)
	s_waitcnt lgkmcnt(0)
	s_add_i32 s0, s19, 1
	s_cmp_ge_i32 s0, s14
	s_mov_b64 s[0:1], -1
	s_barrier
	s_cbranch_scc1 .LBB0_395
	s_and_b32 s0, s16, 0x6000
	v_add_u32_e32 v84, s0, v229
	v_add_u32_e32 v86, v84, v230
	v_add_u32_e32 v87, v84, v231
	ds_read_b128 v[240:243], v228
	ds_read_b128 v[128:131], v86
	ds_read_b128 v[244:247], v228 offset:2048
	ds_read_b128 v[132:135], v87
	ds_read_b128 v[152:155], v228 offset:1024
	ds_read_b128 v[156:159], v228 offset:3072
	ds_read_b128 v[136:139], v86 offset:512
	ds_read_b128 v[148:151], v87 offset:512
	ds_read_b128 v[140:143], v86 offset:4096
	ds_read_b128 v[144:147], v87 offset:4096
	s_lshl_b32 s0, s18, 14
	v_add_u32_e32 v214, s0, v223
	v_add_u32_e32 v215, s0, v224
	v_cvt_pk_bf16_f32 v120, v162, v163
	v_cvt_pk_bf16_f32 v121, v161, v160
	v_cvt_pk_bf16_f32 v122, v167, v166
	v_cvt_pk_bf16_f32 v123, v164, v165
	v_cvt_pk_bf16_f32 v112, v171, v170
	v_cvt_pk_bf16_f32 v113, v169, v168
	v_cvt_pk_bf16_f32 v114, v178, v179
	v_cvt_pk_bf16_f32 v115, v177, v176
	v_cvt_pk_bf16_f32 v124, v175, v174
	v_cvt_pk_bf16_f32 v125, v172, v173
	v_cvt_pk_bf16_f32 v126, v183, v182
	v_cvt_pk_bf16_f32 v127, v181, v180
	v_cvt_pk_bf16_f32 v116, v186, v187
	v_cvt_pk_bf16_f32 v117, v185, v184
	v_cvt_pk_bf16_f32 v118, v191, v190
	v_cvt_pk_bf16_f32 v119, v189, v188
	s_andn2_b64 vcc, exec, s[10:11]
	s_cbranch_vccz .Lh2b_resc

; DEV void diff16_pass(const bf16_t* __restrict__ proj, int qcol, int kcol, int vcol, int q0, f32x4 (&o)[2][8], f32x4 (&l_out)[2], unsigned char* lds) {
;     ...
;   for (int j = 1; j < NT; j += 2) {
;     HALF16(SB2, alB, rfB, SA, alA, rfA, j);
;     if (j + 1 >= NT) break;
;     HALF16(SA, alA, rfA, SB2, alB, rfB, j + 1);
;   }
.LBB0_417:
	s_waitcnt lgkmcnt(8)
	ds_read_b64_tr_b16 v[160:161], v214 offset:2048
	ds_read_b64_tr_b16 v[162:163], v214 offset:6144
	ds_read_b64_tr_b16 v[164:165], v214 offset:10240
	ds_read_b64_tr_b16 v[166:167], v214 offset:14336
	v_mfma_f32_16x16x32_bf16 v[52:55], v[120:123], v[176:179], v[52:55]
	v_exp_f32_e32 v241, v84
	v_exp_f32_e32 v244, v85
	v_mfma_f32_16x16x32_bf16 v[48:51], v[124:127], v[176:179], v[48:51]
	v_exp_f32_e32 v245, v86
	v_exp_f32_e32 v247, v87
	v_mfma_f32_16x16x32_bf16 v[52:55], v[112:115], v[180:183], v[52:55]
	v_exp_f32_e32 v240, v96
	v_mfma_f32_16x16x32_bf16 v[48:51], v[116:119], v[180:183], v[48:51]
	v_exp_f32_e32 v242, v97
	s_waitcnt lgkmcnt(8)
	ds_read_b64_tr_b16 v[168:169], v215 offset:2048
	ds_read_b64_tr_b16 v[170:171], v215 offset:6144
	ds_read_b64_tr_b16 v[172:173], v215 offset:10240
	ds_read_b64_tr_b16 v[174:175], v215 offset:14336
	v_mfma_f32_16x16x32_bf16 v[44:47], v[120:123], v[184:187], v[44:47]
	v_exp_f32_e32 v243, v98
	v_exp_f32_e32 v246, v99
	v_mfma_f32_16x16x32_bf16 v[40:43], v[124:127], v[184:187], v[40:43]
	v_exp_f32_e32 v137, v80
	v_exp_f32_e32 v148, v81
	v_mfma_f32_16x16x32_bf16 v[44:47], v[112:115], v[188:191], v[44:47]
	v_exp_f32_e32 v149, v82
	v_mfma_f32_16x16x32_bf16 v[40:43], v[116:119], v[188:191], v[40:43]
	v_exp_f32_e32 v151, v83
	s_waitcnt lgkmcnt(8)
	ds_read_b64_tr_b16 v[176:177], v214 offset:3072
	ds_read_b64_tr_b16 v[178:179], v214 offset:7168
	ds_read_b64_tr_b16 v[180:181], v214 offset:11264
	ds_read_b64_tr_b16 v[182:183], v214 offset:15360
	v_mfma_f32_16x16x32_bf16 v[32:35], v[120:123], v[140:143], v[32:35]
	v_exp_f32_e32 v136, v89
	v_exp_f32_e32 v139, v90
	v_mfma_f32_16x16x32_bf16 v[36:39], v[124:127], v[140:143], v[36:39]
	v_exp_f32_e32 v150, v91
	v_exp_f32_e32 v129, v92
	v_mfma_f32_16x16x32_bf16 v[32:35], v[112:115], v[144:147], v[32:35]
	v_exp_f32_e32 v138, v95
	v_mfma_f32_16x16x32_bf16 v[36:39], v[116:119], v[144:147], v[36:39]
	v_exp_f32_e32 v128, v104
	s_waitcnt lgkmcnt(8)
	ds_read_b64_tr_b16 v[184:185], v215 offset:3072
	ds_read_b64_tr_b16 v[186:187], v215 offset:7168
	ds_read_b64_tr_b16 v[188:189], v215 offset:11264
	ds_read_b64_tr_b16 v[190:191], v215 offset:15360
	v_mfma_f32_16x16x32_bf16 v[20:23], v[120:123], v[160:163], v[20:23]
	v_exp_f32_e32 v130, v105
	v_exp_f32_e32 v131, v106
	v_mfma_f32_16x16x32_bf16 v[16:19], v[124:127], v[160:163], v[16:19]
	v_exp_f32_e32 v153, v100
	v_exp_f32_e32 v152, v108
	v_mfma_f32_16x16x32_bf16 v[20:23], v[112:115], v[164:167], v[20:23]
	v_exp_f32_e32 v154, v109
	v_mfma_f32_16x16x32_bf16 v[16:19], v[116:119], v[164:167], v[16:19]
	v_exp_f32_e32 v155, v110
	s_waitcnt lgkmcnt(8)
	v_mfma_f32_16x16x32_bf16 v[28:31], v[120:123], v[168:171], v[28:31]
	v_exp_f32_e32 v156, v101
	v_mfma_f32_16x16x32_bf16 v[24:27], v[124:127], v[168:171], v[24:27]
	v_exp_f32_e32 v158, v102
	v_mfma_f32_16x16x32_bf16 v[28:31], v[112:115], v[172:175], v[28:31]
	v_exp_f32_e32 v159, v103
	v_mfma_f32_16x16x32_bf16 v[24:27], v[116:119], v[172:175], v[24:27]
	v_exp_f32_e32 v157, v111
	s_waitcnt lgkmcnt(4)
	v_mfma_f32_16x16x32_bf16 v[12:15], v[120:123], v[176:179], v[12:15]
	v_exp_f32_e32 v132, v88
	v_mfma_f32_16x16x32_bf16 v[8:11], v[124:127], v[176:179], v[8:11]
	v_exp_f32_e32 v134, v93
	v_mfma_f32_16x16x32_bf16 v[12:15], v[112:115], v[180:183], v[12:15]
	v_mfma_f32_16x16x32_bf16 v[8:11], v[116:119], v[180:183], v[8:11]
	s_waitcnt lgkmcnt(0)
	v_mfma_f32_16x16x32_bf16 v[4:7], v[120:123], v[184:187], v[4:7]
	v_exp_f32_e32 v135, v94
	v_mfma_f32_16x16x32_bf16 v[0:3], v[124:127], v[184:187], v[0:3]
	v_exp_f32_e32 v133, v107
	v_mfma_f32_16x16x32_bf16 v[4:7], v[112:115], v[188:191], v[4:7]
	v_mfma_f32_16x16x32_bf16 v[0:3], v[116:119], v[188:191], v[0:3]
	s_waitcnt vmcnt(3)
	s_waitcnt lgkmcnt(0)
	s_add_i32 s15, s15, 0x8000
	s_addk_i32 s16, 0x4000
	s_cmp_ge_i32 s17, s14
	s_cselect_b64 s[0:1], -1, 0
	s_barrier
	s_and_b64 vcc, exec, s[0:1]
	s_mov_b32 s19, s17
	s_cbranch_vccz .LBB0_396
	s_branch .LBB0_419
